# v017_nossm
# baseline (speedup 1.0000x reference)
; __device__ __forceinline__ void ssm_item(const Params& p, int layer, int item, const int tidx) {
;     ...
;     {
;       char* KML = (char*)S;
; #pragma unroll
;       for (int i = 0; i < 4; ++i) {
;         int idx = i * NTHR + tid;
;         *reinterpret_cast<u32x4*>(KML + idx * 16) = *reinterpret_cast<const u32x4*>(KM + (size_t)idx * 8);
;       }
;     }
;     __syncthreads();
;     ...
;         {
;           u32x4 a = *reinterpret_cast<const u32x4*>(kb);
;           if (tA == t0l) a = u32x4{0u, 0u, 0u, 0u};
;           u32x4 bb = *reinterpret_cast<const u32x4*>(ub + (t0l + 1) * 32);
;           acc = __builtin_amdgcn_mfma_f32_32x32x16_bf16(as_bf16x8(a), as_bf16x8(bb), acc, 0, 0, 0);
;         }
; #pragma unroll
;         for (int ks = 0; ks < 8; ++ks) {
;           u32x4 bb = *reinterpret_cast<const u32x4*>(XIN + n * XSTR + (ks * 16 + 8 * half) * 2);
.LBB0_209:
	s_or_b64 exec, exec, s[12:13]
	s_waitcnt lgkmcnt(0)
	s_barrier
	global_load_dwordx4 v[0:3], v[102:103], off
	v_readlane_b32 s12, v254, 16
	v_or_b32_e32 v162, s14, v125
	s_mov_b32 s16, 0
	v_add_u32_e32 v4, s12, v93
	v_mov_b32_e32 v152, v138
	v_mov_b32_e32 v153, v126
	s_waitcnt vmcnt(0)
	ds_write_b128 v4, v[0:3]
	global_load_dwordx4 v[0:3], v[104:105], off
	s_waitcnt vmcnt(0)
	ds_write_b128 v149, v[0:3]
	global_load_dwordx4 v[0:3], v[106:107], off
	s_waitcnt vmcnt(0)
	ds_write_b128 v150, v[0:3]
	global_load_dwordx4 v[0:3], v[108:109], off
	s_waitcnt vmcnt(0)
	ds_write_b128 v151, v[0:3]
	s_waitcnt lgkmcnt(0)
	s_barrier
	ds_read_b128 v[0:3], v147
	ds_read_b128 v[28:31], v148
	ds_read_b128 v[32:35], v148 offset:32
	ds_read_b128 v[36:39], v148 offset:64
	ds_read_b128 v[40:43], v148 offset:96
	ds_read_b128 v[44:47], v148 offset:128
	ds_read_b128 v[48:51], v148 offset:160
	ds_read_b128 v[52:55], v148 offset:192
	ds_read_b128 v[56:59], v148 offset:224
	s_waitcnt lgkmcnt(8)
	v_cndmask_b32_e64 v27, v3, 0, s[8:9]
	v_cndmask_b32_e64 v26, v2, 0, s[8:9]
	v_cndmask_b32_e64 v25, v1, 0, s[8:9]
	v_cndmask_b32_e64 v24, v0, 0, s[8:9]
	s_branch .LBB0_211

; __device__ __forceinline__ void ssm_item(const Params& p, int layer, int item, const int tidx) {
;     ...
;       for (int i = 0; i < 4; ++i) {
;         int rt = wid + 8 * i, t0l = 2 * rt;
;         int tA = t0l + (n >> 4), co = n & 15;
;         u32x4 fa[8];
; #pragma unroll
;         for (int ks = 0; ks < 8; ++ks) fa[ks] = *reinterpret_cast<const u32x4*>(F + ((size_t)(rt * 8 + ks) * 64 + lane) * 8);
;         f32x16 acc;
; #pragma unroll
;         for (int q = 0; q < 16; ++q) acc[q] = 0.f;
;         const char* ub = U + n * USTR + half * 16;
;         const char* kb = KML + (co * 16 + 8 * half) * 2;
; #pragma unroll 4
;         for (int s = 0; s <= t0l; ++s) {
;           u32x4 a = *reinterpret_cast<const u32x4*>(kb + (tA - s) * 512);
;           u32x4 bb = *reinterpret_cast<const u32x4*>(ub + s * 32);
;           acc = __builtin_amdgcn_mfma_f32_32x32x16_bf16(as_bf16x8(a), as_bf16x8(bb), acc, 0, 0, 0);
;         }
.LBB0_211:
	v_lshl_add_u32 v154, s16, 3, v97
	v_lshlrev_b32_e32 v0, 3, v154
	v_ashrrev_i32_e32 v1, 31, v0
	v_or_b32_e32 v4, 1, v0
	v_lshlrev_b64 v[2:3], 10, v[0:1]
	v_ashrrev_i32_e32 v5, 31, v4
	v_lshl_add_u64 v[2:3], v[100:101], 0, v[2:3]
	v_lshlrev_b64 v[4:5], 10, v[4:5]
	v_lshl_add_u64 v[4:5], v[100:101], 0, v[4:5]
	global_load_dwordx4 v[72:75], v[2:3], off
	global_load_dwordx4 v[76:79], v[4:5], off
	v_or_b32_e32 v2, 2, v0
	v_ashrrev_i32_e32 v3, 31, v2
	v_or_b32_e32 v4, 3, v0
	v_lshlrev_b64 v[2:3], 10, v[2:3]
	v_ashrrev_i32_e32 v5, 31, v4
	v_lshl_add_u64 v[2:3], v[100:101], 0, v[2:3]
	v_lshlrev_b64 v[4:5], 10, v[4:5]
	v_lshl_add_u64 v[4:5], v[100:101], 0, v[4:5]
	global_load_dwordx4 v[80:83], v[2:3], off
	global_load_dwordx4 v[84:87], v[4:5], off
	v_or_b32_e32 v2, 4, v0
	v_ashrrev_i32_e32 v3, 31, v2
	v_or_b32_e32 v4, 5, v0
	v_lshlrev_b64 v[2:3], 10, v[2:3]
	v_ashrrev_i32_e32 v5, 31, v4
	v_lshl_add_u64 v[2:3], v[100:101], 0, v[2:3]
	v_lshlrev_b64 v[4:5], 10, v[4:5]
	v_lshl_add_u64 v[4:5], v[100:101], 0, v[4:5]
	global_load_dwordx4 v[88:91], v[2:3], off
	global_load_dwordx4 v[68:71], v[4:5], off
	v_or_b32_e32 v2, 6, v0
	v_ashrrev_i32_e32 v3, 31, v2
	v_or_b32_e32 v0, 7, v0
	v_lshlrev_b64 v[2:3], 10, v[2:3]
	v_ashrrev_i32_e32 v1, 31, v0
	v_lshl_add_u64 v[2:3], v[100:101], 0, v[2:3]
	v_lshlrev_b64 v[0:1], 10, v[0:1]
	v_lshl_add_u64 v[0:1], v[100:101], 0, v[0:1]
	global_load_dwordx4 v[64:67], v[2:3], off
	global_load_dwordx4 v[60:63], v[0:1], off
	v_mov_b32_e32 v15, 0
	v_cmp_lt_i32_e32 vcc, -1, v154
	v_mov_b32_e32 v14, v15
	v_mov_b32_e32 v13, v15
	v_mov_b32_e32 v12, v15
	v_mov_b32_e32 v11, v15
	v_mov_b32_e32 v10, v15
	v_mov_b32_e32 v9, v15
	v_mov_b32_e32 v8, v15
	v_mov_b32_e32 v7, v15
	v_mov_b32_e32 v6, v15
	v_mov_b32_e32 v5, v15
	v_mov_b32_e32 v4, v15
	v_mov_b32_e32 v3, v15
	v_mov_b32_e32 v2, v15
	v_mov_b32_e32 v1, v15
	v_mov_b32_e32 v0, v15
	s_and_saveexec_b64 s[12:13], vcc
	s_cbranch_execz .LBB0_210
	v_max_i32_e32 v0, 0, v153
	v_add_u32_e32 v155, 1, v0
	v_mov_b32_e32 v0, 0
	s_mov_b64 s[14:15], 0
	v_mov_b32_e32 v156, v123
	v_mov_b32_e32 v157, v152
	v_mov_b32_e32 v1, v0
	v_mov_b32_e32 v2, v0
	v_mov_b32_e32 v3, v0
	v_mov_b32_e32 v4, v0
	v_mov_b32_e32 v5, v0
	v_mov_b32_e32 v6, v0
	v_mov_b32_e32 v7, v0
	v_mov_b32_e32 v8, v0
	v_mov_b32_e32 v9, v0
	v_mov_b32_e32 v10, v0
	v_mov_b32_e32 v11, v0
	v_mov_b32_e32 v12, v0
	v_mov_b32_e32 v13, v0
	v_mov_b32_e32 v14, v0
	v_mov_b32_e32 v15, v0
.LBB0_213:
	ds_read_b128 v[158:161], v157
	ds_read_b128 v[164:167], v156
	v_add_u32_e32 v155, -1, v155
	v_cmp_eq_u32_e32 vcc, 0, v155
	v_add_u32_e32 v157, 0xfffffe00, v157
	s_or_b64 s[14:15], vcc, s[14:15]
	s_waitcnt lgkmcnt(0)
	v_mfma_f32_32x32x16_bf16 v[0:15], v[158:161], v[164:167], v[0:15]
	v_add_u32_e32 v156, 32, v156
	s_andn2_b64 exec, exec, s[14:15]
	s_cbranch_execnz .LBB0_213
	s_or_b64 exec, exec, s[14:15]
	s_branch .LBB0_210
